# merged-top barrier plus follower cache invalidate issued right after arrival (leader completes its invalidate before releasing its XCC)
# baseline (speedup 1.0000x reference)
; #define LAS __attribute__((address_space(3)))
; __global__ void __launch_bounds__(512, 2) mk_fwd(Args a) {
;     ...
;     int vbx = bx;
;     { LAS int* vslot = (LAS int*)(lds + RING_BYTES);
;       if (threadIdx.x == 0) { const unsigned my_rank = *(LAS unsigned*)(lds + RING_BYTES + 64); bool ok = (G % 8 == 0) && (my_xcc < 8u);
;           for (int j = 0; j < 8; ++j) ok = ok && (__hip_atomic_load(bar_ctr + 512 + 64 * j, __ATOMIC_RELAXED, __HIP_MEMORY_SCOPE_AGENT) == (unsigned)(G / 8));
;           *vslot = ok ? (int)(my_rank * 8u + my_xcc) : bx; }
;       __syncthreads(); vbx = __builtin_amdgcn_readfirstlane(*vslot); }
.Lmy_gb1_acq:
.Lmy_gb1_done:
.LBB0_82:
	s_or_b64 exec, exec, s[4:5]
	s_barrier
	s_mov_b64 s[4:5], exec
	v_readlane_b32 s0, v255, 0
	v_readlane_b32 s1, v255, 1
	s_and_b64 s[0:1], s[4:5], s[0:1]
	s_mov_b64 exec, s[0:1]
	s_cbranch_execz .LBB0_93
	s_add_i32 s1, 0, 0x20040
	s_and_b32 s0, s3, 15
	v_mov_b32_e32 v0, s1
	s_and_b32 s1, s24, 7
	ds_read_b32 v0, v0
	s_cmp_eq_u32 s1, 0
	s_cselect_b64 s[6:7], -1, 0
	s_cmp_lt_u32 s0, 8
	s_cselect_b64 s[8:9], -1, 0
	s_and_b64 s[6:7], s[6:7], s[8:9]
	s_andn2_b64 vcc, exec, s[6:7]
	s_mov_b64 s[6:7], 0
	s_cbranch_vccnz .LBB0_92
	v_mov_b32_e32 v1, 0
	global_load_dword v2, v1, s[22:23] offset:2048 sc1
	global_load_dword v3, v1, s[22:23] offset:2304 sc1
	global_load_dword v4, v1, s[22:23] offset:2560 sc1
	global_load_dword v5, v1, s[22:23] offset:2816 sc1
	global_load_dword v6, v1, s[22:23] offset:3072 sc1
	global_load_dword v7, v1, s[22:23] offset:3328 sc1
	global_load_dword v8, v1, s[22:23] offset:3584 sc1
	global_load_dword v9, v1, s[22:23] offset:3840 sc1
	s_ashr_i32 s1, s24, 31
	s_lshr_b32 s1, s1, 29
	s_add_i32 s1, s24, s1
	s_ashr_i32 s1, s1, 3
	s_waitcnt vmcnt(0)
	v_xor_b32_e32 v2, s1, v2
	v_xor_b32_e32 v3, s1, v3
	v_xor_b32_e32 v4, s1, v4
	v_xor_b32_e32 v5, s1, v5
	v_xor_b32_e32 v6, s1, v6
	v_xor_b32_e32 v7, s1, v7
	v_xor_b32_e32 v8, s1, v8
	v_xor_b32_e32 v9, s1, v9
	v_or3_b32 v2, v2, v3, v4
	v_or3_b32 v5, v5, v6, v7
	v_or3_b32 v2, v2, v5, v8
	v_or_b32_e32 v2, v2, v9
	v_cmp_eq_u32_e64 s[6:7], 0, v2
